# MIX2 epilogue: 16 serialized load-wait-store round trips replaced by 8-deep software pipeline
# speedup vs baseline: 1.0083x; 1.0083x over previous
; __device__ __forceinline__ void store8(bf16_t* dst, const float* v) { u32x4 w; w.x = pk2(v[0], v[1]); w.y = pk2(v[2], v[3]); w.z = pk2(v[4], v[5]); w.w = pk2(v[6], v[7]); *(u32x4*)dst = w; }
; __device__ __forceinline__ void load8(const bf16_t* src, float* v) { const u32x4 w = *(const u32x4*)src; v[0] = bf_lo(w.x); v[1] = bf_hi(w.x); v[2] = bf_lo(w.y); v[3] = bf_hi(w.y); v[4] = bf_lo(w.z); v[5] = bf_hi(w.z); v[6] = bf_lo(w.w); v[7] = bf_hi(w.w); }
;     __device__ __forceinline__ void operator()(const pg8::f32x4 (&acc)[2][2][4][2], const pg8::Unit& u, int wr, int wc, int fr, int fq) const {
;     ...
; #pragma unroll
;         for (int ai = 0; ai < 2; ++ai)
; #pragma unroll
;             for (int m = 0; m < 4; ++m) {
;                 const int row = u.pm * 256 + ai * 128 + wr * 64 + m * 16 + fr;
;                 const int bb = row >> 13, ss = row & 8191;
;                 float ssq = 0.f;
;                 float rs = 1.f;
;                 if constexpr (KIND == EK_Q || KIND == EK_KV) rs = __builtin_amdgcn_rsqf(a.ssq0[row] * (1.f / 512.f) + EPS);
;                 if constexpr (KIND == EK_FIN) rs = __builtin_amdgcn_rsqf(a.ssq0[row] * (1.f / 2048.f) + EPS);
; #pragma unroll
;                 for (int bj = 0; bj < 2; ++bj) {
;                     const int cl = bj * 128 + wc * 32 + fq * 8;
;                     float v[8];
; #pragma unroll
;                     for (int j = 0; j < 4; ++j) { v[j] = acc[ai][bj][m][0][j]; v[4 + j] = acc[ai][bj][m][1][j]; }
;     ...
;                     } else if constexpr (KIND == EK_MIX2) {
;                         const size_t off = (size_t)row * 2048 + pn * 256 + cl; float g[8], pr[8]; load8(a.g0 + off, g); load8(a.o0 + off, pr);
; #pragma unroll
;                         for (int j = 0; j < 8; ++j) v[j] = pr[j] + v[j] * g[j];
;                         store8(a.o0 + off, v);
.LBB0_1076:
	v_lshl_add_u32 v148, s26, 8, v137
	s_lshl_b32 s26, s27, 9
	v_lshlrev_b32_e32 v148, 12, v148
	v_lshl_add_u32 v149, v136, 1, s26
	v_add_u32_e32 v148, v148, v149
	global_load_dwordx4 v[154:157], v148, s[12:13]
	global_load_dwordx4 v[158:161], v148, s[10:11]
	global_load_dwordx4 v[162:165], v148, s[12:13] offset:256
	global_load_dwordx4 v[168:171], v148, s[10:11] offset:256
	v_add_u32_e32 v149, 0x10000, v148
	global_load_dwordx4 v[172:175], v149, s[12:13]
	global_load_dwordx4 v[182:185], v149, s[10:11]
	global_load_dwordx4 v[186:189], v149, s[12:13] offset:256
	global_load_dwordx4 v[190:193], v149, s[10:11] offset:256
	v_add_u32_e32 v149, 0x20000, v148
	global_load_dwordx4 v[194:197], v149, s[12:13]
	global_load_dwordx4 v[198:201], v149, s[10:11]
	global_load_dwordx4 v[202:205], v149, s[12:13] offset:256
	global_load_dwordx4 v[206:209], v149, s[10:11] offset:256
	v_add_u32_e32 v149, 0x30000, v148
	global_load_dwordx4 v[210:213], v149, s[12:13]
	global_load_dwordx4 v[214:217], v149, s[10:11]
	global_load_dwordx4 v[218:221], v149, s[12:13] offset:256
	global_load_dwordx4 v[222:225], v149, s[10:11] offset:256
	s_waitcnt vmcnt(14)
	v_lshlrev_b32_e32 v226, 16, v154
	v_and_b32_e32 v154, 0xffff0000, v154
	v_lshlrev_b32_e32 v227, 16, v158
	v_and_b32_e32 v158, 0xffff0000, v158
	v_fma_f32 v124, v124, v226, v227
	v_fma_f32 v125, v125, v154, v158
	v_lshlrev_b32_e32 v228, 16, v155
	v_and_b32_e32 v155, 0xffff0000, v155
	v_lshlrev_b32_e32 v229, 16, v159
	v_and_b32_e32 v159, 0xffff0000, v159
	v_fma_f32 v126, v126, v228, v229
	v_fma_f32 v127, v127, v155, v159
	v_lshlrev_b32_e32 v226, 16, v156
	v_and_b32_e32 v156, 0xffff0000, v156
	v_lshlrev_b32_e32 v227, 16, v160
	v_and_b32_e32 v160, 0xffff0000, v160
	v_fma_f32 v120, v120, v226, v227
	v_fma_f32 v121, v121, v156, v160
	v_lshlrev_b32_e32 v228, 16, v157
	v_and_b32_e32 v157, 0xffff0000, v157
	v_lshlrev_b32_e32 v229, 16, v161
	v_and_b32_e32 v161, 0xffff0000, v161
	v_fma_f32 v122, v122, v228, v229
	v_fma_f32 v123, v123, v157, v161
	v_cvt_pk_bf16_f32 v124, v124, v125
	v_cvt_pk_bf16_f32 v125, v126, v127
	v_cvt_pk_bf16_f32 v126, v120, v121
	v_cvt_pk_bf16_f32 v127, v122, v123
	global_store_dwordx4 v148, v[124:127], s[10:11]
	v_add_u32_e32 v149, 0x80000, v148
	global_load_dwordx4 v[154:157], v149, s[12:13]
	global_load_dwordx4 v[158:161], v149, s[10:11]
	s_waitcnt vmcnt(15)
	v_lshlrev_b32_e32 v226, 16, v162
	v_and_b32_e32 v162, 0xffff0000, v162
	v_lshlrev_b32_e32 v227, 16, v168
	v_and_b32_e32 v168, 0xffff0000, v168
	v_fma_f32 v116, v116, v226, v227
	v_fma_f32 v117, v117, v162, v168
	v_lshlrev_b32_e32 v228, 16, v163
	v_and_b32_e32 v163, 0xffff0000, v163
	v_lshlrev_b32_e32 v229, 16, v169
	v_and_b32_e32 v169, 0xffff0000, v169
	v_fma_f32 v118, v118, v228, v229
	v_fma_f32 v119, v119, v163, v169
	v_lshlrev_b32_e32 v226, 16, v164
	v_and_b32_e32 v164, 0xffff0000, v164
	v_lshlrev_b32_e32 v227, 16, v170
	v_and_b32_e32 v170, 0xffff0000, v170
	v_fma_f32 v112, v112, v226, v227
	v_fma_f32 v113, v113, v164, v170
	v_lshlrev_b32_e32 v228, 16, v165
	v_and_b32_e32 v165, 0xffff0000, v165
	v_lshlrev_b32_e32 v229, 16, v171
	v_and_b32_e32 v171, 0xffff0000, v171
	v_fma_f32 v114, v114, v228, v229
	v_fma_f32 v115, v115, v165, v171
	v_cvt_pk_bf16_f32 v116, v116, v117
	v_cvt_pk_bf16_f32 v117, v118, v119
	v_cvt_pk_bf16_f32 v118, v112, v113
	v_cvt_pk_bf16_f32 v119, v114, v115
	global_store_dwordx4 v148, v[116:119], s[10:11] offset:256
	global_load_dwordx4 v[162:165], v149, s[12:13] offset:256
	global_load_dwordx4 v[168:171], v149, s[10:11] offset:256
	s_waitcnt vmcnt(16)
	v_lshlrev_b32_e32 v226, 16, v172
	v_and_b32_e32 v172, 0xffff0000, v172
	v_lshlrev_b32_e32 v227, 16, v182
	v_and_b32_e32 v182, 0xffff0000, v182
	v_fma_f32 v108, v108, v226, v227
	v_fma_f32 v109, v109, v172, v182
	v_lshlrev_b32_e32 v228, 16, v173
	v_and_b32_e32 v173, 0xffff0000, v173
	v_lshlrev_b32_e32 v229, 16, v183
	v_and_b32_e32 v183, 0xffff0000, v183
	v_fma_f32 v110, v110, v228, v229
	v_fma_f32 v111, v111, v173, v183
	v_lshlrev_b32_e32 v226, 16, v174
	v_and_b32_e32 v174, 0xffff0000, v174
	v_lshlrev_b32_e32 v227, 16, v184
	v_and_b32_e32 v184, 0xffff0000, v184
	v_fma_f32 v104, v104, v226, v227
	v_fma_f32 v105, v105, v174, v184
	v_lshlrev_b32_e32 v228, 16, v175
	v_and_b32_e32 v175, 0xffff0000, v175
	v_lshlrev_b32_e32 v229, 16, v185
	v_and_b32_e32 v185, 0xffff0000, v185
	v_fma_f32 v106, v106, v228, v229
	v_fma_f32 v107, v107, v175, v185
	v_cvt_pk_bf16_f32 v108, v108, v109
	v_cvt_pk_bf16_f32 v109, v110, v111
	v_cvt_pk_bf16_f32 v110, v104, v105
	v_cvt_pk_bf16_f32 v111, v106, v107
	v_add_u32_e32 v153, 0x10000, v148
	global_store_dwordx4 v153, v[108:111], s[10:11]
	v_add_u32_e32 v149, 0x90000, v148
	global_load_dwordx4 v[172:175], v149, s[12:13]
	global_load_dwordx4 v[182:185], v149, s[10:11]
	s_waitcnt vmcnt(17)
	v_lshlrev_b32_e32 v226, 16, v186
	v_and_b32_e32 v186, 0xffff0000, v186
	v_lshlrev_b32_e32 v227, 16, v190
	v_and_b32_e32 v190, 0xffff0000, v190
	v_fma_f32 v100, v100, v226, v227
	v_fma_f32 v101, v101, v186, v190
	v_lshlrev_b32_e32 v228, 16, v187
	v_and_b32_e32 v187, 0xffff0000, v187
	v_lshlrev_b32_e32 v229, 16, v191
	v_and_b32_e32 v191, 0xffff0000, v191
	v_fma_f32 v102, v102, v228, v229
	v_fma_f32 v103, v103, v187, v191
	v_lshlrev_b32_e32 v226, 16, v188
	v_and_b32_e32 v188, 0xffff0000, v188
	v_lshlrev_b32_e32 v227, 16, v192
	v_and_b32_e32 v192, 0xffff0000, v192
	v_fma_f32 v96, v96, v226, v227
	v_fma_f32 v97, v97, v188, v192
	v_lshlrev_b32_e32 v228, 16, v189
	v_and_b32_e32 v189, 0xffff0000, v189
	v_lshlrev_b32_e32 v229, 16, v193
	v_and_b32_e32 v193, 0xffff0000, v193
	v_fma_f32 v98, v98, v228, v229
	v_fma_f32 v99, v99, v189, v193
	v_cvt_pk_bf16_f32 v100, v100, v101
	v_cvt_pk_bf16_f32 v101, v102, v103
	v_cvt_pk_bf16_f32 v102, v96, v97
	v_cvt_pk_bf16_f32 v103, v98, v99
	global_store_dwordx4 v153, v[100:103], s[10:11] offset:256
	global_load_dwordx4 v[186:189], v149, s[12:13] offset:256
	global_load_dwordx4 v[190:193], v149, s[10:11] offset:256
	s_waitcnt vmcnt(18)
; __device__ __forceinline__ void store8(bf16_t* dst, const float* v) { u32x4 w; w.x = pk2(v[0], v[1]); w.y = pk2(v[2], v[3]); w.z = pk2(v[4], v[5]); w.w = pk2(v[6], v[7]); *(u32x4*)dst = w; }
; __device__ __forceinline__ void load8(const bf16_t* src, float* v) { const u32x4 w = *(const u32x4*)src; v[0] = bf_lo(w.x); v[1] = bf_hi(w.x); v[2] = bf_lo(w.y); v[3] = bf_hi(w.y); v[4] = bf_lo(w.z); v[5] = bf_hi(w.z); v[6] = bf_lo(w.w); v[7] = bf_hi(w.w); }
;     __device__ __forceinline__ void operator()(const pg8::f32x4 (&acc)[2][2][4][2], const pg8::Unit& u, int wr, int wc, int fr, int fq) const {
;     ...
; #pragma unroll
;         for (int ai = 0; ai < 2; ++ai)
; #pragma unroll
;             for (int m = 0; m < 4; ++m) {
;                 const int row = u.pm * 256 + ai * 128 + wr * 64 + m * 16 + fr;
;                 const int bb = row >> 13, ss = row & 8191;
;                 float ssq = 0.f;
;                 float rs = 1.f;
;                 if constexpr (KIND == EK_Q || KIND == EK_KV) rs = __builtin_amdgcn_rsqf(a.ssq0[row] * (1.f / 512.f) + EPS);
;                 if constexpr (KIND == EK_FIN) rs = __builtin_amdgcn_rsqf(a.ssq0[row] * (1.f / 2048.f) + EPS);
; #pragma unroll
;                 for (int bj = 0; bj < 2; ++bj) {
;                     const int cl = bj * 128 + wc * 32 + fq * 8;
;                     float v[8];
; #pragma unroll
;                     for (int j = 0; j < 4; ++j) { v[j] = acc[ai][bj][m][0][j]; v[4 + j] = acc[ai][bj][m][1][j]; }
;     ...
;                     } else if constexpr (KIND == EK_MIX2) {
;                         const size_t off = (size_t)row * 2048 + pn * 256 + cl; float g[8], pr[8]; load8(a.g0 + off, g); load8(a.o0 + off, pr);
; #pragma unroll
;                         for (int j = 0; j < 8; ++j) v[j] = pr[j] + v[j] * g[j];
;                         store8(a.o0 + off, v);
	v_lshlrev_b32_e32 v226, 16, v194
	v_and_b32_e32 v194, 0xffff0000, v194
	v_lshlrev_b32_e32 v227, 16, v198
	v_and_b32_e32 v198, 0xffff0000, v198
	v_fma_f32 v92, v92, v226, v227
	v_fma_f32 v93, v93, v194, v198
	v_lshlrev_b32_e32 v228, 16, v195
	v_and_b32_e32 v195, 0xffff0000, v195
	v_lshlrev_b32_e32 v229, 16, v199
	v_and_b32_e32 v199, 0xffff0000, v199
	v_fma_f32 v94, v94, v228, v229
	v_fma_f32 v95, v95, v195, v199
	v_lshlrev_b32_e32 v226, 16, v196
	v_and_b32_e32 v196, 0xffff0000, v196
	v_lshlrev_b32_e32 v227, 16, v200
	v_and_b32_e32 v200, 0xffff0000, v200
	v_fma_f32 v88, v88, v226, v227
	v_fma_f32 v89, v89, v196, v200
	v_lshlrev_b32_e32 v228, 16, v197
	v_and_b32_e32 v197, 0xffff0000, v197
	v_lshlrev_b32_e32 v229, 16, v201
	v_and_b32_e32 v201, 0xffff0000, v201
	v_fma_f32 v90, v90, v228, v229
	v_fma_f32 v91, v91, v197, v201
	v_cvt_pk_bf16_f32 v92, v92, v93
	v_cvt_pk_bf16_f32 v93, v94, v95
	v_cvt_pk_bf16_f32 v94, v88, v89
	v_cvt_pk_bf16_f32 v95, v90, v91
	v_add_u32_e32 v153, 0x20000, v148
	global_store_dwordx4 v153, v[92:95], s[10:11]
	v_add_u32_e32 v149, 0xa0000, v148
	global_load_dwordx4 v[194:197], v149, s[12:13]
	global_load_dwordx4 v[198:201], v149, s[10:11]
	s_waitcnt vmcnt(19)
	v_lshlrev_b32_e32 v226, 16, v202
	v_and_b32_e32 v202, 0xffff0000, v202
	v_lshlrev_b32_e32 v227, 16, v206
	v_and_b32_e32 v206, 0xffff0000, v206
	v_fma_f32 v84, v84, v226, v227
	v_fma_f32 v85, v85, v202, v206
	v_lshlrev_b32_e32 v228, 16, v203
	v_and_b32_e32 v203, 0xffff0000, v203
	v_lshlrev_b32_e32 v229, 16, v207
	v_and_b32_e32 v207, 0xffff0000, v207
	v_fma_f32 v86, v86, v228, v229
	v_fma_f32 v87, v87, v203, v207
	v_lshlrev_b32_e32 v226, 16, v204
	v_and_b32_e32 v204, 0xffff0000, v204
	v_lshlrev_b32_e32 v227, 16, v208
	v_and_b32_e32 v208, 0xffff0000, v208
	v_fma_f32 v80, v80, v226, v227
	v_fma_f32 v81, v81, v204, v208
	v_lshlrev_b32_e32 v228, 16, v205
	v_and_b32_e32 v205, 0xffff0000, v205
	v_lshlrev_b32_e32 v229, 16, v209
	v_and_b32_e32 v209, 0xffff0000, v209
	v_fma_f32 v82, v82, v228, v229
	v_fma_f32 v83, v83, v205, v209
	v_cvt_pk_bf16_f32 v84, v84, v85
	v_cvt_pk_bf16_f32 v85, v86, v87
	v_cvt_pk_bf16_f32 v86, v80, v81
	v_cvt_pk_bf16_f32 v87, v82, v83
	global_store_dwordx4 v153, v[84:87], s[10:11] offset:256
	global_load_dwordx4 v[202:205], v149, s[12:13] offset:256
	global_load_dwordx4 v[206:209], v149, s[10:11] offset:256
	s_waitcnt vmcnt(20)
	v_lshlrev_b32_e32 v226, 16, v210
	v_and_b32_e32 v210, 0xffff0000, v210
	v_lshlrev_b32_e32 v227, 16, v214
	v_and_b32_e32 v214, 0xffff0000, v214
	v_fma_f32 v76, v76, v226, v227
	v_fma_f32 v77, v77, v210, v214
	v_lshlrev_b32_e32 v228, 16, v211
	v_and_b32_e32 v211, 0xffff0000, v211
	v_lshlrev_b32_e32 v229, 16, v215
	v_and_b32_e32 v215, 0xffff0000, v215
	v_fma_f32 v78, v78, v228, v229
	v_fma_f32 v79, v79, v211, v215
	v_lshlrev_b32_e32 v226, 16, v212
	v_and_b32_e32 v212, 0xffff0000, v212
	v_lshlrev_b32_e32 v227, 16, v216
	v_and_b32_e32 v216, 0xffff0000, v216
	v_fma_f32 v72, v72, v226, v227
	v_fma_f32 v73, v73, v212, v216
	v_lshlrev_b32_e32 v228, 16, v213
	v_and_b32_e32 v213, 0xffff0000, v213
	v_lshlrev_b32_e32 v229, 16, v217
	v_and_b32_e32 v217, 0xffff0000, v217
	v_fma_f32 v74, v74, v228, v229
	v_fma_f32 v75, v75, v213, v217
	v_cvt_pk_bf16_f32 v76, v76, v77
	v_cvt_pk_bf16_f32 v77, v78, v79
	v_cvt_pk_bf16_f32 v78, v72, v73
	v_cvt_pk_bf16_f32 v79, v74, v75
	v_add_u32_e32 v153, 0x30000, v148
	global_store_dwordx4 v153, v[76:79], s[10:11]
	v_add_u32_e32 v149, 0xb0000, v148
	global_load_dwordx4 v[210:213], v149, s[12:13]
	global_load_dwordx4 v[214:217], v149, s[10:11]
	s_waitcnt vmcnt(21)
	v_lshlrev_b32_e32 v226, 16, v218
	v_and_b32_e32 v218, 0xffff0000, v218
	v_lshlrev_b32_e32 v227, 16, v222
	v_and_b32_e32 v222, 0xffff0000, v222
	v_fma_f32 v68, v68, v226, v227
	v_fma_f32 v69, v69, v218, v222
	v_lshlrev_b32_e32 v228, 16, v219
	v_and_b32_e32 v219, 0xffff0000, v219
	v_lshlrev_b32_e32 v229, 16, v223
	v_and_b32_e32 v223, 0xffff0000, v223
	v_fma_f32 v70, v70, v228, v229
	v_fma_f32 v71, v71, v219, v223
	v_lshlrev_b32_e32 v226, 16, v220
	v_and_b32_e32 v220, 0xffff0000, v220
	v_lshlrev_b32_e32 v227, 16, v224
	v_and_b32_e32 v224, 0xffff0000, v224
	v_fma_f32 v64, v64, v226, v227
	v_fma_f32 v65, v65, v220, v224
	v_lshlrev_b32_e32 v228, 16, v221
	v_and_b32_e32 v221, 0xffff0000, v221
	v_lshlrev_b32_e32 v229, 16, v225
	v_and_b32_e32 v225, 0xffff0000, v225
	v_fma_f32 v66, v66, v228, v229
	v_fma_f32 v67, v67, v221, v225
	v_cvt_pk_bf16_f32 v68, v68, v69
	v_cvt_pk_bf16_f32 v69, v70, v71
	v_cvt_pk_bf16_f32 v70, v64, v65
	v_cvt_pk_bf16_f32 v71, v66, v67
	global_store_dwordx4 v153, v[68:71], s[10:11] offset:256
	global_load_dwordx4 v[218:221], v149, s[12:13] offset:256
	global_load_dwordx4 v[222:225], v149, s[10:11] offset:256
	s_waitcnt vmcnt(21)
	v_lshlrev_b32_e32 v226, 16, v154
	v_and_b32_e32 v154, 0xffff0000, v154
	v_lshlrev_b32_e32 v227, 16, v158
	v_and_b32_e32 v158, 0xffff0000, v158
	v_fma_f32 v60, v60, v226, v227
	v_fma_f32 v61, v61, v154, v158
	v_lshlrev_b32_e32 v228, 16, v155
	v_and_b32_e32 v155, 0xffff0000, v155
	v_lshlrev_b32_e32 v229, 16, v159
	v_and_b32_e32 v159, 0xffff0000, v159
	v_fma_f32 v62, v62, v228, v229
	v_fma_f32 v63, v63, v155, v159
	v_lshlrev_b32_e32 v226, 16, v156
	v_and_b32_e32 v156, 0xffff0000, v156
	v_lshlrev_b32_e32 v227, 16, v160
	v_and_b32_e32 v160, 0xffff0000, v160
	v_fma_f32 v56, v56, v226, v227
	v_fma_f32 v57, v57, v156, v160
	v_lshlrev_b32_e32 v228, 16, v157
	v_and_b32_e32 v157, 0xffff0000, v157
	v_lshlrev_b32_e32 v229, 16, v161
	v_and_b32_e32 v161, 0xffff0000, v161
	v_fma_f32 v58, v58, v228, v229
	v_fma_f32 v59, v59, v157, v161
	v_cvt_pk_bf16_f32 v60, v60, v61
	v_cvt_pk_bf16_f32 v61, v62, v63
	v_cvt_pk_bf16_f32 v62, v56, v57
	v_cvt_pk_bf16_f32 v63, v58, v59
	v_add_u32_e32 v153, 0x80000, v148
	global_store_dwordx4 v153, v[60:63], s[10:11]
	s_waitcnt vmcnt(19)
; __device__ __forceinline__ void store8(bf16_t* dst, const float* v) { u32x4 w; w.x = pk2(v[0], v[1]); w.y = pk2(v[2], v[3]); w.z = pk2(v[4], v[5]); w.w = pk2(v[6], v[7]); *(u32x4*)dst = w; }
; __device__ __forceinline__ void load8(const bf16_t* src, float* v) { const u32x4 w = *(const u32x4*)src; v[0] = bf_lo(w.x); v[1] = bf_hi(w.x); v[2] = bf_lo(w.y); v[3] = bf_hi(w.y); v[4] = bf_lo(w.z); v[5] = bf_hi(w.z); v[6] = bf_lo(w.w); v[7] = bf_hi(w.w); }
;     __device__ __forceinline__ void operator()(const pg8::f32x4 (&acc)[2][2][4][2], const pg8::Unit& u, int wr, int wc, int fr, int fq) const {
;     ...
; #pragma unroll
;         for (int ai = 0; ai < 2; ++ai)
; #pragma unroll
;             for (int m = 0; m < 4; ++m) {
;                 const int row = u.pm * 256 + ai * 128 + wr * 64 + m * 16 + fr;
;                 const int bb = row >> 13, ss = row & 8191;
;                 float ssq = 0.f;
;                 float rs = 1.f;
;                 if constexpr (KIND == EK_Q || KIND == EK_KV) rs = __builtin_amdgcn_rsqf(a.ssq0[row] * (1.f / 512.f) + EPS);
;                 if constexpr (KIND == EK_FIN) rs = __builtin_amdgcn_rsqf(a.ssq0[row] * (1.f / 2048.f) + EPS);
; #pragma unroll
;                 for (int bj = 0; bj < 2; ++bj) {
;                     const int cl = bj * 128 + wc * 32 + fq * 8;
;                     float v[8];
; #pragma unroll
;                     for (int j = 0; j < 4; ++j) { v[j] = acc[ai][bj][m][0][j]; v[4 + j] = acc[ai][bj][m][1][j]; }
;     ...
;                     } else if constexpr (KIND == EK_MIX2) {
;                         const size_t off = (size_t)row * 2048 + pn * 256 + cl; float g[8], pr[8]; load8(a.g0 + off, g); load8(a.o0 + off, pr);
; #pragma unroll
;                         for (int j = 0; j < 8; ++j) v[j] = pr[j] + v[j] * g[j];
;                         store8(a.o0 + off, v);
	v_lshlrev_b32_e32 v226, 16, v162
	v_and_b32_e32 v162, 0xffff0000, v162
	v_lshlrev_b32_e32 v227, 16, v168
	v_and_b32_e32 v168, 0xffff0000, v168
	v_fma_f32 v52, v52, v226, v227
	v_fma_f32 v53, v53, v162, v168
	v_lshlrev_b32_e32 v228, 16, v163
	v_and_b32_e32 v163, 0xffff0000, v163
	v_lshlrev_b32_e32 v229, 16, v169
	v_and_b32_e32 v169, 0xffff0000, v169
	v_fma_f32 v54, v54, v228, v229
	v_fma_f32 v55, v55, v163, v169
	v_lshlrev_b32_e32 v226, 16, v164
	v_and_b32_e32 v164, 0xffff0000, v164
	v_lshlrev_b32_e32 v227, 16, v170
	v_and_b32_e32 v170, 0xffff0000, v170
	v_fma_f32 v48, v48, v226, v227
	v_fma_f32 v49, v49, v164, v170
	v_lshlrev_b32_e32 v228, 16, v165
	v_and_b32_e32 v165, 0xffff0000, v165
	v_lshlrev_b32_e32 v229, 16, v171
	v_and_b32_e32 v171, 0xffff0000, v171
	v_fma_f32 v50, v50, v228, v229
	v_fma_f32 v51, v51, v165, v171
	v_cvt_pk_bf16_f32 v52, v52, v53
	v_cvt_pk_bf16_f32 v53, v54, v55
	v_cvt_pk_bf16_f32 v54, v48, v49
	v_cvt_pk_bf16_f32 v55, v50, v51
	global_store_dwordx4 v153, v[52:55], s[10:11] offset:256
	s_waitcnt vmcnt(17)
	v_lshlrev_b32_e32 v226, 16, v172
	v_and_b32_e32 v172, 0xffff0000, v172
	v_lshlrev_b32_e32 v227, 16, v182
	v_and_b32_e32 v182, 0xffff0000, v182
	v_fma_f32 v44, v44, v226, v227
	v_fma_f32 v45, v45, v172, v182
	v_lshlrev_b32_e32 v228, 16, v173
	v_and_b32_e32 v173, 0xffff0000, v173
	v_lshlrev_b32_e32 v229, 16, v183
	v_and_b32_e32 v183, 0xffff0000, v183
	v_fma_f32 v46, v46, v228, v229
	v_fma_f32 v47, v47, v173, v183
	v_lshlrev_b32_e32 v226, 16, v174
	v_and_b32_e32 v174, 0xffff0000, v174
	v_lshlrev_b32_e32 v227, 16, v184
	v_and_b32_e32 v184, 0xffff0000, v184
	v_fma_f32 v40, v40, v226, v227
	v_fma_f32 v41, v41, v174, v184
	v_lshlrev_b32_e32 v228, 16, v175
	v_and_b32_e32 v175, 0xffff0000, v175
	v_lshlrev_b32_e32 v229, 16, v185
	v_and_b32_e32 v185, 0xffff0000, v185
	v_fma_f32 v42, v42, v228, v229
	v_fma_f32 v43, v43, v175, v185
	v_cvt_pk_bf16_f32 v44, v44, v45
	v_cvt_pk_bf16_f32 v45, v46, v47
	v_cvt_pk_bf16_f32 v46, v40, v41
	v_cvt_pk_bf16_f32 v47, v42, v43
	v_add_u32_e32 v153, 0x90000, v148
	global_store_dwordx4 v153, v[44:47], s[10:11]
	s_waitcnt vmcnt(15)
	v_lshlrev_b32_e32 v226, 16, v186
	v_and_b32_e32 v186, 0xffff0000, v186
	v_lshlrev_b32_e32 v227, 16, v190
	v_and_b32_e32 v190, 0xffff0000, v190
	v_fma_f32 v36, v36, v226, v227
	v_fma_f32 v37, v37, v186, v190
	v_lshlrev_b32_e32 v228, 16, v187
	v_and_b32_e32 v187, 0xffff0000, v187
	v_lshlrev_b32_e32 v229, 16, v191
	v_and_b32_e32 v191, 0xffff0000, v191
	v_fma_f32 v38, v38, v228, v229
	v_fma_f32 v39, v39, v187, v191
	v_lshlrev_b32_e32 v226, 16, v188
	v_and_b32_e32 v188, 0xffff0000, v188
	v_lshlrev_b32_e32 v227, 16, v192
	v_and_b32_e32 v192, 0xffff0000, v192
	v_fma_f32 v32, v32, v226, v227
	v_fma_f32 v33, v33, v188, v192
	v_lshlrev_b32_e32 v228, 16, v189
	v_and_b32_e32 v189, 0xffff0000, v189
	v_lshlrev_b32_e32 v229, 16, v193
	v_and_b32_e32 v193, 0xffff0000, v193
	v_fma_f32 v34, v34, v228, v229
	v_fma_f32 v35, v35, v189, v193
	v_cvt_pk_bf16_f32 v36, v36, v37
	v_cvt_pk_bf16_f32 v37, v38, v39
	v_cvt_pk_bf16_f32 v38, v32, v33
	v_cvt_pk_bf16_f32 v39, v34, v35
	global_store_dwordx4 v153, v[36:39], s[10:11] offset:256
	s_waitcnt vmcnt(13)
	v_lshlrev_b32_e32 v226, 16, v194
	v_and_b32_e32 v194, 0xffff0000, v194
	v_lshlrev_b32_e32 v227, 16, v198
	v_and_b32_e32 v198, 0xffff0000, v198
	v_fma_f32 v28, v28, v226, v227
	v_fma_f32 v29, v29, v194, v198
	v_lshlrev_b32_e32 v228, 16, v195
	v_and_b32_e32 v195, 0xffff0000, v195
	v_lshlrev_b32_e32 v229, 16, v199
	v_and_b32_e32 v199, 0xffff0000, v199
	v_fma_f32 v30, v30, v228, v229
	v_fma_f32 v31, v31, v195, v199
	v_lshlrev_b32_e32 v226, 16, v196
	v_and_b32_e32 v196, 0xffff0000, v196
	v_lshlrev_b32_e32 v227, 16, v200
	v_and_b32_e32 v200, 0xffff0000, v200
	v_fma_f32 v24, v24, v226, v227
	v_fma_f32 v25, v25, v196, v200
	v_lshlrev_b32_e32 v228, 16, v197
	v_and_b32_e32 v197, 0xffff0000, v197
	v_lshlrev_b32_e32 v229, 16, v201
	v_and_b32_e32 v201, 0xffff0000, v201
	v_fma_f32 v26, v26, v228, v229
	v_fma_f32 v27, v27, v197, v201
	v_cvt_pk_bf16_f32 v28, v28, v29
	v_cvt_pk_bf16_f32 v29, v30, v31
	v_cvt_pk_bf16_f32 v30, v24, v25
	v_cvt_pk_bf16_f32 v31, v26, v27
	v_add_u32_e32 v153, 0xa0000, v148
	global_store_dwordx4 v153, v[28:31], s[10:11]
	s_waitcnt vmcnt(11)
; #define PG8_BAR __builtin_amdgcn_s_barrier()
; __device__ __forceinline__ void store8(bf16_t* dst, const float* v) { u32x4 w; w.x = pk2(v[0], v[1]); w.y = pk2(v[2], v[3]); w.z = pk2(v[4], v[5]); w.w = pk2(v[6], v[7]); *(u32x4*)dst = w; }
; template <class Epi, class Sched, bool ALIGN_EPI = false, bool SP2 = false>
; __device__ __forceinline__ void gemm_phase(PG8_LAS unsigned char* lds, const Gemm g, const Sched& S, const Epi& E) {
;     ...
;         if (!has_next) break;
; #pragma unroll
;         for (int a = 0; a < 2; ++a)
; #pragma unroll
;             for (int b = 0; b < 2; ++b)
; #pragma unroll
;                 for (int m = 0; m < 4; ++m)
; #pragma unroll
;                     for (int n = 0; n < 2; ++n) acc[a][b][m][n] = (f32x4){0.f, 0.f, 0.f, 0.f};
;         cur = nxt; cA = nA; cB = nB; ++ui;
;         if constexpr (ALIGN_EPI) { if (wr == 1) PG8_BAR; }
;     __device__ __forceinline__ void operator()(const pg8::f32x4 (&acc)[2][2][4][2], const pg8::Unit& u, int wr, int wc, int fr, int fq) const {
;     ...
; #pragma unroll
;         for (int ai = 0; ai < 2; ++ai)
; #pragma unroll
;             for (int m = 0; m < 4; ++m) {
;                 const int row = u.pm * 256 + ai * 128 + wr * 64 + m * 16 + fr;
;                 const int bb = row >> 13, ss = row & 8191;
;                 float ssq = 0.f;
;                 float rs = 1.f;
;                 if constexpr (KIND == EK_Q || KIND == EK_KV) rs = __builtin_amdgcn_rsqf(a.ssq0[row] * (1.f / 512.f) + EPS);
;                 if constexpr (KIND == EK_FIN) rs = __builtin_amdgcn_rsqf(a.ssq0[row] * (1.f / 2048.f) + EPS);
; #pragma unroll
;                 for (int bj = 0; bj < 2; ++bj) {
;                     const int cl = bj * 128 + wc * 32 + fq * 8;
;                     float v[8];
; #pragma unroll
;                     for (int j = 0; j < 4; ++j) { v[j] = acc[ai][bj][m][0][j]; v[4 + j] = acc[ai][bj][m][1][j]; }
;     ...
;                     } else if constexpr (KIND == EK_MIX2) {
;                         const size_t off = (size_t)row * 2048 + pn * 256 + cl; float g[8], pr[8]; load8(a.g0 + off, g); load8(a.o0 + off, pr);
; #pragma unroll
;                         for (int j = 0; j < 8; ++j) v[j] = pr[j] + v[j] * g[j];
;                         store8(a.o0 + off, v);
	v_lshlrev_b32_e32 v226, 16, v202
	v_and_b32_e32 v202, 0xffff0000, v202
	v_lshlrev_b32_e32 v227, 16, v206
	v_and_b32_e32 v206, 0xffff0000, v206
	v_fma_f32 v20, v20, v226, v227
	v_fma_f32 v21, v21, v202, v206
	v_lshlrev_b32_e32 v228, 16, v203
	v_and_b32_e32 v203, 0xffff0000, v203
	v_lshlrev_b32_e32 v229, 16, v207
	v_and_b32_e32 v207, 0xffff0000, v207
	v_fma_f32 v22, v22, v228, v229
	v_fma_f32 v23, v23, v203, v207
	v_lshlrev_b32_e32 v226, 16, v204
	v_and_b32_e32 v204, 0xffff0000, v204
	v_lshlrev_b32_e32 v227, 16, v208
	v_and_b32_e32 v208, 0xffff0000, v208
	v_fma_f32 v16, v16, v226, v227
	v_fma_f32 v17, v17, v204, v208
	v_lshlrev_b32_e32 v228, 16, v205
	v_and_b32_e32 v205, 0xffff0000, v205
	v_lshlrev_b32_e32 v229, 16, v209
	v_and_b32_e32 v209, 0xffff0000, v209
	v_fma_f32 v18, v18, v228, v229
	v_fma_f32 v19, v19, v205, v209
	v_cvt_pk_bf16_f32 v20, v20, v21
	v_cvt_pk_bf16_f32 v21, v22, v23
	v_cvt_pk_bf16_f32 v22, v16, v17
	v_cvt_pk_bf16_f32 v23, v18, v19
	global_store_dwordx4 v153, v[20:23], s[10:11] offset:256
	s_waitcnt vmcnt(9)
	v_lshlrev_b32_e32 v226, 16, v210
	v_and_b32_e32 v210, 0xffff0000, v210
	v_lshlrev_b32_e32 v227, 16, v214
	v_and_b32_e32 v214, 0xffff0000, v214
	v_fma_f32 v12, v12, v226, v227
	v_fma_f32 v13, v13, v210, v214
	v_lshlrev_b32_e32 v228, 16, v211
	v_and_b32_e32 v211, 0xffff0000, v211
	v_lshlrev_b32_e32 v229, 16, v215
	v_and_b32_e32 v215, 0xffff0000, v215
	v_fma_f32 v14, v14, v228, v229
	v_fma_f32 v15, v15, v211, v215
	v_lshlrev_b32_e32 v226, 16, v212
	v_and_b32_e32 v212, 0xffff0000, v212
	v_lshlrev_b32_e32 v227, 16, v216
	v_and_b32_e32 v216, 0xffff0000, v216
	v_fma_f32 v8, v8, v226, v227
	v_fma_f32 v9, v9, v212, v216
	v_lshlrev_b32_e32 v228, 16, v213
	v_and_b32_e32 v213, 0xffff0000, v213
	v_lshlrev_b32_e32 v229, 16, v217
	v_and_b32_e32 v217, 0xffff0000, v217
	v_fma_f32 v10, v10, v228, v229
	v_fma_f32 v11, v11, v213, v217
	v_cvt_pk_bf16_f32 v12, v12, v13
	v_cvt_pk_bf16_f32 v13, v14, v15
	v_cvt_pk_bf16_f32 v14, v8, v9
	v_cvt_pk_bf16_f32 v15, v10, v11
	v_add_u32_e32 v153, 0xb0000, v148
	global_store_dwordx4 v153, v[12:15], s[10:11]
	s_waitcnt vmcnt(7)
	v_lshlrev_b32_e32 v226, 16, v218
	v_and_b32_e32 v218, 0xffff0000, v218
	v_lshlrev_b32_e32 v227, 16, v222
	v_and_b32_e32 v222, 0xffff0000, v222
	v_fma_f32 v4, v4, v226, v227
	v_fma_f32 v5, v5, v218, v222
	v_lshlrev_b32_e32 v228, 16, v219
	v_and_b32_e32 v219, 0xffff0000, v219
	v_lshlrev_b32_e32 v229, 16, v223
	v_and_b32_e32 v223, 0xffff0000, v223
	v_fma_f32 v6, v6, v228, v229
	v_fma_f32 v7, v7, v219, v223
	v_lshlrev_b32_e32 v226, 16, v220
	v_and_b32_e32 v220, 0xffff0000, v220
	v_lshlrev_b32_e32 v227, 16, v224
	v_and_b32_e32 v224, 0xffff0000, v224
	v_fma_f32 v0, v0, v226, v227
	v_fma_f32 v1, v1, v220, v224
	v_lshlrev_b32_e32 v228, 16, v221
	v_and_b32_e32 v221, 0xffff0000, v221
	v_lshlrev_b32_e32 v229, 16, v225
	v_and_b32_e32 v225, 0xffff0000, v225
	v_fma_f32 v2, v2, v228, v229
	v_fma_f32 v3, v3, v221, v225
	v_cvt_pk_bf16_f32 v4, v4, v5
	v_cvt_pk_bf16_f32 v5, v6, v7
	v_cvt_pk_bf16_f32 v6, v0, v1
	v_cvt_pk_bf16_f32 v7, v2, v3
	global_store_dwordx4 v153, v[4:7], s[10:11] offset:256
	s_andn2_b64 vcc, exec, s[6:7]
	s_mov_b64 s[6:7], -1
	s_cbranch_vccnz .LBB0_1065
	s_andn2_b64 vcc, exec, s[8:9]
	s_cbranch_vccnz .LBB0_1064
	s_barrier
	s_branch .LBB0_1064
